# v34 plus krope_gemm A-fragment prefetch with counted waits
# baseline (speedup 1.0000x reference)
.LBB0_219:
	v_add_u32_e32 v2, s0, v172
	v_ashrrev_i32_e32 v3, 31, v2
	v_lshlrev_b64 v[2:3], 12, v[2:3]
	v_lshl_add_u64 v[190:191], v[162:163], 0, v[2:3]
	global_load_dwordx4 v[18:21], v[190:191], off
	global_load_dwordx4 v[182:185], v[190:191], off offset:32
	global_load_dwordx4 v[186:189], v[190:191], off offset:64
	global_load_dwordx4 v[192:195], v[190:191], off offset:96
	global_load_dwordx4 v[206:209], v[190:191], off offset:128
	global_load_dwordx4 v[210:213], v[190:191], off offset:160
	global_load_dwordx4 v[216:219], v[190:191], off offset:192
	global_load_dwordx4 v[220:223], v[190:191], off offset:224
	global_load_dwordx4 v[224:227], v[190:191], off offset:256
	global_load_dwordx4 v[228:231], v[190:191], off offset:288
	global_load_dwordx4 v[232:235], v[190:191], off offset:320
	global_load_dwordx4 v[236:239], v[190:191], off offset:352
	global_load_dwordx4 v[240:243], v[190:191], off offset:384
	global_load_dwordx4 v[244:247], v[190:191], off offset:416
	s_add_i32 s1, s1, s80
	s_waitcnt vmcnt(13)
	v_mfma_f32_32x32x16_bf16 v[2:17], v[18:21], v[46:49], 0
	v_mfma_f32_32x32x16_bf16 v[18:33], v[18:21], v[34:37], 0
	s_waitcnt vmcnt(12)
	v_mfma_f32_32x32x16_bf16 v[2:17], v[182:185], v[42:45], v[2:17]
	v_mfma_f32_32x32x16_bf16 v[18:33], v[182:185], v[38:41], v[18:33]
	global_load_dwordx4 v[182:185], v[190:191], off offset:448
	s_waitcnt vmcnt(12)
	v_mfma_f32_32x32x16_bf16 v[2:17], v[186:189], v[50:53], v[2:17]
	v_mfma_f32_32x32x16_bf16 v[18:33], v[186:189], v[58:61], v[18:33]
	global_load_dwordx4 v[186:189], v[190:191], off offset:480
	s_waitcnt vmcnt(12)
	v_mfma_f32_32x32x16_bf16 v[2:17], v[192:195], v[54:57], v[2:17]
	v_mfma_f32_32x32x16_bf16 v[18:33], v[192:195], v[62:65], v[18:33]
	s_waitcnt vmcnt(11)
	v_mfma_f32_32x32x16_bf16 v[2:17], v[206:209], v[66:69], v[2:17]
	v_mfma_f32_32x32x16_bf16 v[18:33], v[206:209], v[74:77], v[18:33]
	s_waitcnt vmcnt(10)
	v_mfma_f32_32x32x16_bf16 v[2:17], v[210:213], v[70:73], v[2:17]
	v_mfma_f32_32x32x16_bf16 v[18:33], v[210:213], v[78:81], v[18:33]
	s_waitcnt vmcnt(9)
	v_mfma_f32_32x32x16_bf16 v[2:17], v[216:219], v[82:85], v[2:17]
	v_mfma_f32_32x32x16_bf16 v[18:33], v[216:219], v[90:93], v[18:33]
	s_waitcnt vmcnt(8)
	v_mfma_f32_32x32x16_bf16 v[2:17], v[220:223], v[86:89], v[2:17]
	v_mfma_f32_32x32x16_bf16 v[18:33], v[220:223], v[94:97], v[18:33]
	s_waitcnt vmcnt(7)
	v_mfma_f32_32x32x16_bf16 v[2:17], v[224:227], v[98:101], v[2:17]
	v_mfma_f32_32x32x16_bf16 v[18:33], v[224:227], v[106:109], v[18:33]
	s_waitcnt vmcnt(6)
	v_mfma_f32_32x32x16_bf16 v[2:17], v[228:231], v[102:105], v[2:17]
	v_mfma_f32_32x32x16_bf16 v[18:33], v[228:231], v[110:113], v[18:33]
	s_waitcnt vmcnt(5)
	v_mfma_f32_32x32x16_bf16 v[2:17], v[232:235], v[114:117], v[2:17]
	v_mfma_f32_32x32x16_bf16 v[18:33], v[232:235], v[122:125], v[18:33]
	s_waitcnt vmcnt(4)
	v_mfma_f32_32x32x16_bf16 v[2:17], v[236:239], v[118:121], v[2:17]
	v_mfma_f32_32x32x16_bf16 v[18:33], v[236:239], v[126:129], v[18:33]
	s_waitcnt vmcnt(3)
	v_mfma_f32_32x32x16_bf16 v[2:17], v[240:243], v[130:133], v[2:17]
	v_mfma_f32_32x32x16_bf16 v[18:33], v[240:243], v[138:141], v[18:33]
	s_waitcnt vmcnt(2)
	v_mfma_f32_32x32x16_bf16 v[2:17], v[244:247], v[134:137], v[2:17]
	v_mfma_f32_32x32x16_bf16 v[18:33], v[244:247], v[142:145], v[18:33]
	s_waitcnt vmcnt(1)
	v_mfma_f32_32x32x16_bf16 v[2:17], v[182:185], v[146:149], v[2:17]
	v_mfma_f32_32x32x16_bf16 v[18:33], v[182:185], v[154:157], v[18:33]
	s_waitcnt vmcnt(0)
	v_mfma_f32_32x32x16_bf16 v[2:17], v[186:189], v[150:153], v[2:17]
	v_mfma_f32_32x32x16_bf16 v[18:33], v[186:189], v[158:161], v[18:33]
	v_add_u32_e32 v186, s0, v175
	v_ashrrev_i32_e32 v187, 31, v186
	v_lshl_add_u64 v[188:189], v[186:187], 2, s[8:9]
	s_nop 10
	ds_write2st64_b32 v176, v2, v3 offset1:1
	ds_write2st64_b32 v176, v18, v19 offset0:16 offset1:17
	ds_write2st64_b32 v176, v4, v5 offset0:2 offset1:3
	ds_write2st64_b32 v176, v20, v21 offset0:18 offset1:19
	ds_write2st64_b32 v176, v6, v7 offset0:4 offset1:5
	ds_write2st64_b32 v176, v22, v23 offset0:20 offset1:21
	ds_write2st64_b32 v176, v8, v9 offset0:6 offset1:7
	ds_write2st64_b32 v176, v24, v25 offset0:22 offset1:23
	ds_write2st64_b32 v176, v10, v11 offset0:8 offset1:9
	ds_write2st64_b32 v176, v26, v27 offset0:24 offset1:25
	ds_write2st64_b32 v176, v12, v13 offset0:10 offset1:11
	ds_write2st64_b32 v176, v28, v29 offset0:26 offset1:27
	ds_write2st64_b32 v176, v14, v15 offset0:12 offset1:13
	ds_write2st64_b32 v176, v30, v31 offset0:28 offset1:29
	ds_write2st64_b32 v176, v16, v17 offset0:14 offset1:15
	ds_write2st64_b32 v176, v32, v33 offset0:30 offset1:31
	s_waitcnt lgkmcnt(0)
	s_barrier
	global_load_dword v14, v[188:189], off
	v_add_u32_e32 v2, s0, v174
	ds_read2st64_b32 v[6:7], v177 offset1:32
	ds_read2st64_b32 v[8:9], v177 offset0:64 offset1:96
	ds_read2st64_b32 v[10:11], v177 offset0:128 offset1:160
	ds_read2st64_b32 v[12:13], v177 offset0:192 offset1:224
	v_ashrrev_i32_e32 v3, 31, v2
	v_lshl_add_u64 v[4:5], v[2:3], 2, s[8:9]
	s_waitcnt lgkmcnt(3)
	v_add_f32_e32 v3, 0, v6
	v_add_f32_e32 v3, v3, v7
	s_waitcnt lgkmcnt(2)
	v_add_f32_e32 v3, v3, v8
	v_add_f32_e32 v3, v3, v9
	s_waitcnt lgkmcnt(1)
	v_add_f32_e32 v3, v3, v10
	v_add_f32_e32 v3, v3, v11
	s_waitcnt lgkmcnt(0)
	v_add_f32_e32 v3, v3, v12
	v_add_f32_e32 v3, v3, v13
	s_waitcnt vmcnt(0)
	v_fmamk_f32 v6, v14, 0x3a000000, v203
	v_mul_f32_e32 v7, 0x4b800000, v6
	v_cmp_gt_f32_e32 vcc, s12, v6
	s_nop 1
	v_cndmask_b32_e32 v6, v6, v7, vcc
	v_rsq_f32_e32 v6, v6
	s_nop 0
	v_mul_f32_e32 v7, 0x45800000, v6
	v_cndmask_b32_e32 v6, v6, v7, vcc
	v_mul_f32_e32 v3, v3, v6
	v_cvt_pk_bf16_f32 v3, v3, v3
	global_load_dword v20, v[4:5], off
	v_mov_b64_e32 v[4:5], s[6:7]
	v_mad_i64_i32 v[8:9], s[4:5], v186, s10, v[4:5]
	v_add_u32_e32 v6, s0, v173
	v_lshl_add_u64 v[8:9], v[164:165], 1, v[8:9]
	v_ashrrev_i32_e32 v7, 31, v6
	v_add_co_u32_e32 v8, vcc, s11, v8
	ds_read2st64_b32 v[12:13], v179 offset1:32
	ds_read2st64_b32 v[14:15], v179 offset0:64 offset1:96
	ds_read2st64_b32 v[16:17], v179 offset0:128 offset1:160
	ds_read2st64_b32 v[18:19], v179 offset0:192 offset1:224
	v_lshl_add_u64 v[10:11], v[6:7], 2, s[8:9]
	v_addc_co_u32_e32 v9, vcc, 0, v9, vcc
	global_store_short v[8:9], v3, off
	s_waitcnt lgkmcnt(3)
	v_add_f32_e32 v3, 0, v12
	v_add_f32_e32 v3, v3, v13
	s_waitcnt lgkmcnt(2)
	v_add_f32_e32 v3, v3, v14
	v_add_f32_e32 v3, v3, v15
	s_waitcnt lgkmcnt(1)
	v_add_f32_e32 v3, v3, v16
	v_add_f32_e32 v3, v3, v17
	s_waitcnt lgkmcnt(0)
	v_add_f32_e32 v3, v3, v18
	v_add_f32_e32 v3, v3, v19
	s_waitcnt vmcnt(1)
	v_fmamk_f32 v7, v20, 0x3a000000, v203
	v_mul_f32_e32 v8, 0x4b800000, v7
	v_cmp_gt_f32_e32 vcc, s12, v7
	s_nop 1
	v_cndmask_b32_e32 v7, v7, v8, vcc
	v_rsq_f32_e32 v7, v7
	s_nop 0
	v_mul_f32_e32 v8, 0x45800000, v7
	v_cndmask_b32_e32 v7, v7, v8, vcc
	v_mul_f32_e32 v3, v3, v7
	v_cvt_pk_bf16_f32 v7, v3, v3
	global_load_dword v20, v[10:11], off
	v_mad_i64_i32 v[2:3], s[4:5], v2, s10, v[4:5]
	v_lshl_add_u64 v[2:3], v[166:167], 1, v[2:3]
	v_add_co_u32_e32 v2, vcc, s11, v2
	ds_read2st64_b32 v[12:13], v180 offset1:32
	ds_read2st64_b32 v[14:15], v180 offset0:64 offset1:96
	ds_read2st64_b32 v[16:17], v180 offset0:128 offset1:160
	ds_read2st64_b32 v[18:19], v180 offset0:192 offset1:224
	v_addc_co_u32_e32 v3, vcc, 0, v3, vcc
	global_store_short v[2:3], v7, off
	s_waitcnt lgkmcnt(3)
	v_add_f32_e32 v2, 0, v12
	v_add_f32_e32 v2, v2, v13
	s_waitcnt lgkmcnt(2)
	v_add_f32_e32 v2, v2, v14
	v_add_f32_e32 v2, v2, v15
	s_waitcnt lgkmcnt(1)
	v_add_f32_e32 v2, v2, v16
	v_add_u32_e32 v8, s0, v0
	v_add_f32_e32 v2, v2, v17
	v_ashrrev_i32_e32 v9, 31, v8
	s_waitcnt lgkmcnt(0)
	v_add_f32_e32 v2, v2, v18
	v_lshl_add_u64 v[10:11], v[8:9], 2, s[8:9]
	v_add_f32_e32 v2, v2, v19
	s_add_i32 s0, s0, s2
	s_cmpk_lt_i32 s1, 0x100
	s_waitcnt vmcnt(1)
	v_fmamk_f32 v3, v20, 0x3a000000, v203
	v_mul_f32_e32 v7, 0x4b800000, v3
	v_cmp_gt_f32_e32 vcc, s12, v3
	s_nop 1
	v_cndmask_b32_e32 v3, v3, v7, vcc
	v_rsq_f32_e32 v3, v3
	s_nop 0
	v_mul_f32_e32 v7, 0x45800000, v3
	v_cndmask_b32_e32 v3, v3, v7, vcc
	v_mul_f32_e32 v2, v2, v3
	v_cvt_pk_bf16_f32 v14, v2, v2
	global_load_dword v15, v[10:11], off
	v_mad_i64_i32 v[2:3], s[4:5], v6, s10, v[4:5]
	v_lshl_add_u64 v[2:3], v[168:169], 1, v[2:3]
	v_mad_i64_i32 v[4:5], s[4:5], v8, s10, v[4:5]
	v_add_co_u32_e32 v2, vcc, s11, v2
	v_lshl_add_u64 v[4:5], v[170:171], 1, v[4:5]
	s_nop 0
	v_addc_co_u32_e32 v3, vcc, 0, v3, vcc
	v_add_co_u32_e32 v4, vcc, 0x2000, v4
	ds_read2st64_b32 v[6:7], v181 offset1:32
	ds_read2st64_b32 v[8:9], v181 offset0:64 offset1:96
	ds_read2st64_b32 v[10:11], v181 offset0:128 offset1:160
	ds_read2st64_b32 v[12:13], v181 offset0:192 offset1:224
	v_addc_co_u32_e32 v5, vcc, 0, v5, vcc
	global_store_short v[2:3], v14, off
	s_waitcnt lgkmcnt(3)
	v_add_f32_e32 v2, 0, v6
	v_add_f32_e32 v2, v2, v7
	s_waitcnt lgkmcnt(2)
	v_add_f32_e32 v2, v2, v8
	v_add_f32_e32 v2, v2, v9
	s_waitcnt lgkmcnt(1)
	v_add_f32_e32 v2, v2, v10
	v_add_f32_e32 v2, v2, v11
	s_waitcnt lgkmcnt(0)
	v_add_f32_e32 v2, v2, v12
	v_add_f32_e32 v2, v2, v13
	s_waitcnt vmcnt(1)
	v_fmamk_f32 v3, v15, 0x3a000000, v203
	v_mul_f32_e32 v6, 0x4b800000, v3
	v_cmp_gt_f32_e32 vcc, s12, v3
	s_nop 1
	v_cndmask_b32_e32 v3, v3, v6, vcc
	v_rsq_f32_e32 v3, v3
	s_nop 0
	v_mul_f32_e32 v6, 0x45800000, v3
	v_cndmask_b32_e32 v3, v3, v6, vcc
	v_mul_f32_e32 v2, v2, v3
	v_cvt_pk_bf16_f32 v2, v2, v2
	global_store_short v[4:5], v2, off
	s_barrier
	s_cbranch_scc1 .LBB0_219
